# attention item epilogue: all 8 sub-layer-norm weight loads issued together under the LDS exchange; store ladder no longer waits per pair
# baseline (speedup 1.0000x reference)
; __device__ __forceinline__ void attn_item(const Params& p, unsigned char* smem, int b, int h, int qb, float lam) {
;     ...
;   const float l_tot = l_run + __shfl_xor(l_run, 32);
;   const float inv = 1.f / l_tot;
; #pragma unroll
;   for (int d = 0; d < 4; ++d)
; #pragma unroll
;     for (int g = 0; g < 4; ++g) {
;       float4 o4 = make_float4(oacc[d][4 * g] * inv, oacc[d][4 * g + 1] * inv, oacc[d][4 * g + 2] * inv, oacc[d][4 * g + 3] * inv);
;       *(float4*)(sO + ((map * 64 + r0 + l31) * 132 + d * 32 + 8 * g + 4 * hf)) = o4;
;     }
;   __syncthreads();
;   {
;     const int q = tid >> 2, qq = tid & 3;
;     const float4* o0 = (const float4*)(sO + (q * 132 + qq * 32)); const float4* o1 = (const float4*)(sO + ((64 + q) * 132 + qq * 32));
;     float ss = 0.f;
; #pragma unroll
;     for (int i = 0; i < 8; ++i) {
;       float4 a = o0[i], c = o1[i];
;       float dx = a.x - lam * c.x, dy = a.y - lam * c.y, dz = a.z - lam * c.z, dw = a.w - lam * c.w;
;       ss += dx * dx + dy * dy + dz * dz + dw * dw;
;     }
;     ss += __shfl_xor(ss, 1); ss += __shfl_xor(ss, 2);
.LBB0_323:
	ds_bpermute_b32 v64, v208, v217
	v_or3_b32 v65, v188, v200, v181
	v_mul_lo_u32 v65, v65, s31
	v_add3_u32 v65, 16, v65, v178
	v_ashrrev_i32_e32 v88, 2, v199
	s_waitcnt lgkmcnt(0)
	v_add_f32_e32 v64, v217, v64
	v_div_scale_f32 v66, s[14:15], v64, v64, 1.0
	v_rcp_f32_e32 v67, v66
	v_div_scale_f32 v68, vcc, 1.0, v64, 1.0
	s_mov_b64 s[14:15], 0
	v_fma_f32 v69, -v66, v67, 1.0
	v_fmac_f32_e32 v67, v69, v67
	v_mul_f32_e32 v69, v68, v67
	v_fma_f32 v70, -v66, v69, v68
	v_fmac_f32_e32 v69, v70, v67
	v_fma_f32 v66, -v66, v69, v68
	v_div_fmas_f32 v66, v66, v67, v69
	v_div_fixup_f32 v64, v66, v64, 1.0
	v_pk_mul_f32 v[0:1], v[0:1], v[64:65] op_sel_hi:[1,0]
	v_pk_mul_f32 v[2:3], v[2:3], v[64:65] op_sel_hi:[1,0]
	ds_write_b128 v65, v[0:3] offset:384
	v_pk_mul_f32 v[0:1], v[4:5], v[64:65] op_sel_hi:[1,0]
	v_pk_mul_f32 v[2:3], v[6:7], v[64:65] op_sel_hi:[1,0]
	ds_write_b128 v65, v[0:3] offset:416
	v_pk_mul_f32 v[0:1], v[8:9], v[64:65] op_sel_hi:[1,0]
	v_pk_mul_f32 v[2:3], v[10:11], v[64:65] op_sel_hi:[1,0]
	ds_write_b128 v65, v[0:3] offset:448
	v_pk_mul_f32 v[0:1], v[12:13], v[64:65] op_sel_hi:[1,0]
	v_pk_mul_f32 v[2:3], v[14:15], v[64:65] op_sel_hi:[1,0]
	v_pk_mul_f32 v[48:49], v[48:49], v[64:65] op_sel_hi:[1,0]
	v_pk_mul_f32 v[50:51], v[50:51], v[64:65] op_sel_hi:[1,0]
	v_pk_mul_f32 v[32:33], v[32:33], v[64:65] op_sel_hi:[1,0]
	v_pk_mul_f32 v[34:35], v[34:35], v[64:65] op_sel_hi:[1,0]
	v_pk_mul_f32 v[16:17], v[16:17], v[64:65] op_sel_hi:[1,0]
	v_pk_mul_f32 v[18:19], v[18:19], v[64:65] op_sel_hi:[1,0]
	ds_write_b128 v65, v[0:3] offset:480
	v_lshlrev_b32_e32 v0, 5, v199
	ds_write_b128 v65, v[48:51]
	v_pk_mul_f32 v[48:49], v[52:53], v[64:65] op_sel_hi:[1,0]
	v_pk_mul_f32 v[50:51], v[54:55], v[64:65] op_sel_hi:[1,0]
	ds_write_b128 v65, v[32:35] offset:128
	v_pk_mul_f32 v[32:33], v[36:37], v[64:65] op_sel_hi:[1,0]
	v_pk_mul_f32 v[34:35], v[38:39], v[64:65] op_sel_hi:[1,0]
	ds_write_b128 v65, v[16:19] offset:256
	v_pk_mul_f32 v[16:17], v[20:21], v[64:65] op_sel_hi:[1,0]
	v_pk_mul_f32 v[18:19], v[22:23], v[64:65] op_sel_hi:[1,0]
	v_and_b32_e32 v89, 0x60, v0
	ds_write_b128 v65, v[48:51] offset:32
	v_pk_mul_f32 v[48:49], v[56:57], v[64:65] op_sel_hi:[1,0]
	v_pk_mul_f32 v[50:51], v[58:59], v[64:65] op_sel_hi:[1,0]
	ds_write_b128 v65, v[32:35] offset:160
	v_pk_mul_f32 v[32:33], v[40:41], v[64:65] op_sel_hi:[1,0]
	v_pk_mul_f32 v[34:35], v[42:43], v[64:65] op_sel_hi:[1,0]
	ds_write_b128 v65, v[16:19] offset:288
	v_pk_mul_f32 v[16:17], v[24:25], v[64:65] op_sel_hi:[1,0]
	v_pk_mul_f32 v[18:19], v[26:27], v[64:65] op_sel_hi:[1,0]
	v_mul_lo_u32 v0, v88, s31
	v_lshlrev_b32_e32 v90, 2, v89
	ds_write_b128 v65, v[48:51] offset:64
	v_pk_mul_f32 v[48:49], v[60:61], v[64:65] op_sel_hi:[1,0]
	v_pk_mul_f32 v[50:51], v[62:63], v[64:65] op_sel_hi:[1,0]
	ds_write_b128 v65, v[32:35] offset:192
	v_pk_mul_f32 v[32:33], v[44:45], v[64:65] op_sel_hi:[1,0]
	v_pk_mul_f32 v[34:35], v[46:47], v[64:65] op_sel_hi:[1,0]
	ds_write_b128 v65, v[16:19] offset:320
	v_pk_mul_f32 v[16:17], v[28:29], v[64:65] op_sel_hi:[1,0]
	v_pk_mul_f32 v[18:19], v[30:31], v[64:65] op_sel_hi:[1,0]
	v_add3_u32 v91, 16, v0, v90
	ds_write_b128 v65, v[48:51] offset:96
	ds_write_b128 v65, v[32:35] offset:224
	ds_write_b128 v65, v[16:19] offset:352
	s_waitcnt lgkmcnt(0)
	s_barrier
	ds_read_b128 v[4:7], v91 offset:33824
	ds_read_b128 v[0:3], v91 offset:33840
	ds_read_b128 v[12:15], v91 offset:32
	ds_read_b128 v[8:11], v91 offset:48
	ds_read_b128 v[16:19], v91
	ds_read_b128 v[20:23], v91 offset:16
	v_lshlrev_b32_e32 v178, 1, v89
	s_waitcnt lgkmcnt(5)
	v_mov_b32_e32 v24, v4
	s_waitcnt lgkmcnt(4)
	v_mov_b32_e32 v25, v0
	s_waitcnt lgkmcnt(3)
	v_mov_b32_e32 v26, v12
	s_waitcnt lgkmcnt(2)
	v_mov_b32_e32 v27, v8
	v_pk_fma_f32 v[24:25], v[176:177], v[24:25], v[26:27] neg_lo:[1,0,0] neg_hi:[1,0,0]
	v_mov_b32_e32 v26, v5
	v_mov_b32_e32 v27, v1
	v_mov_b32_e32 v28, v13
	v_mov_b32_e32 v29, v9
	v_pk_fma_f32 v[26:27], v[176:177], v[26:27], v[28:29] neg_lo:[1,0,0] neg_hi:[1,0,0]
	v_mov_b32_e32 v28, v6
	v_mov_b32_e32 v29, v2
	v_mov_b32_e32 v30, v14
	v_mov_b32_e32 v31, v10
	v_pk_mul_f32 v[26:27], v[26:27], v[26:27]
	v_pk_fma_f32 v[28:29], v[176:177], v[28:29], v[30:31] neg_lo:[1,0,0] neg_hi:[1,0,0]
	v_mov_b32_e32 v30, v7
	v_mov_b32_e32 v31, v3
	v_mov_b32_e32 v32, v15
	v_mov_b32_e32 v33, v11
	v_pk_fma_f32 v[24:25], v[24:25], v[24:25], v[26:27]
	v_pk_fma_f32 v[30:31], v[176:177], v[30:31], v[32:33] neg_lo:[1,0,0] neg_hi:[1,0,0]
	v_pk_fma_f32 v[24:25], v[28:29], v[28:29], v[24:25]
	v_pk_fma_f32 v[4:5], v[176:177], v[4:5], v[12:13] neg_lo:[1,0,0] neg_hi:[1,0,0]
	v_pk_fma_f32 v[24:25], v[30:31], v[30:31], v[24:25]
	ds_read_b128 v[26:29], v91 offset:33856
	ds_read_b128 v[30:33], v91 offset:80
	ds_read_b128 v[34:37], v91 offset:33872
	ds_read_b128 v[38:41], v91 offset:64
	ds_read_b128 v[42:45], v91 offset:33856
	s_waitcnt lgkmcnt(4)
	v_mov_b32_e32 v58, v26
	s_waitcnt lgkmcnt(3)
	v_mov_b32_e32 v61, v30
	s_waitcnt lgkmcnt(2)
	v_mov_b32_e32 v59, v34
	v_mov_b32_e32 v34, v27
	s_waitcnt lgkmcnt(1)
; __device__ __forceinline__ void attn_item(const Params& p, unsigned char* smem, int b, int h, int qb, float lam) {
;     ...
;   {
;     const int q = tid >> 2, qq = tid & 3;
;     const float4* o0 = (const float4*)(sO + (q * 132 + qq * 32)); const float4* o1 = (const float4*)(sO + ((64 + q) * 132 + qq * 32));
;     float ss = 0.f;
; #pragma unroll
;     for (int i = 0; i < 8; ++i) {
;       float4 a = o0[i], c = o1[i];
;       float dx = a.x - lam * c.x, dy = a.y - lam * c.y, dz = a.z - lam * c.z, dw = a.w - lam * c.w;
;       ss += dx * dx + dy * dy + dz * dz + dw * dw;
;     }
;     ss += __shfl_xor(ss, 1); ss += __shfl_xor(ss, 2);
;     const float rsn = rsqrtf(ss * (1.f / 128.f) + 1e-6f) * 0.8f;
;     const float4* nw = (const float4*)(p.attn_norm_w + qq * 32);
	v_mov_b32_e32 v30, v39
	v_mov_b32_e32 v60, v38
	v_pk_fma_f32 v[26:27], v[176:177], v[34:35], v[30:31] neg_lo:[1,0,0] neg_hi:[1,0,0]
	v_pk_fma_f32 v[58:59], v[176:177], v[58:59], v[60:61] neg_lo:[1,0,0] neg_hi:[1,0,0]
	v_mov_b32_e32 v30, v28
	v_mov_b32_e32 v31, v36
	v_mov_b32_e32 v34, v40
	v_mov_b32_e32 v35, v32
	v_pk_mul_f32 v[26:27], v[26:27], v[26:27]
	v_pk_fma_f32 v[30:31], v[176:177], v[30:31], v[34:35] neg_lo:[1,0,0] neg_hi:[1,0,0]
	v_mov_b32_e32 v36, v29
	v_mov_b32_e32 v32, v41
	v_pk_fma_f32 v[26:27], v[58:59], v[58:59], v[26:27]
	v_pk_fma_f32 v[28:29], v[176:177], v[36:37], v[32:33] neg_lo:[1,0,0] neg_hi:[1,0,0]
	v_pk_fma_f32 v[26:27], v[30:31], v[30:31], v[26:27]
	ds_read_b128 v[46:49], v91 offset:33872
	ds_read_b128 v[50:53], v91 offset:64
	ds_read_b128 v[54:57], v91 offset:80
	v_pk_fma_f32 v[82:83], v[28:29], v[28:29], v[26:27]
	ds_read_b128 v[26:29], v91 offset:112
	ds_read_b128 v[30:33], v91 offset:33888
	global_load_dwordx4 v[34:37], v90, s[6:7] offset:16
	global_load_dwordx4 v[38:41], v90, s[6:7]
	global_load_dwordx4 v[96:99], v90, s[6:7] offset:32
	global_load_dwordx4 v[100:103], v90, s[6:7] offset:48
	global_load_dwordx4 v[104:107], v90, s[6:7] offset:64
	global_load_dwordx4 v[108:111], v90, s[6:7] offset:80
	global_load_dwordx4 v[112:115], v90, s[6:7] offset:96
	global_load_dwordx4 v[116:119], v90, s[6:7] offset:112
	ds_read_b128 v[58:61], v91 offset:33904
	ds_read_b128 v[62:65], v91 offset:96
	ds_read_b128 v[66:69], v91 offset:33888
	ds_read_b128 v[70:73], v91 offset:33904
	ds_read_b128 v[74:77], v91 offset:96
	s_waitcnt lgkmcnt(4)
	v_mov_b32_e32 v85, v58
	v_mov_b32_e32 v87, v26
	v_mov_b32_e32 v58, v31
	s_waitcnt lgkmcnt(3)
	v_mov_b32_e32 v26, v63
	v_mov_b32_e32 v84, v30
	v_mov_b32_e32 v86, v62
	v_pk_fma_f32 v[26:27], v[176:177], v[58:59], v[26:27] neg_lo:[1,0,0] neg_hi:[1,0,0]
	v_pk_fma_f32 v[84:85], v[176:177], v[84:85], v[86:87] neg_lo:[1,0,0] neg_hi:[1,0,0]
	v_mov_b32_e32 v30, v32
	v_mov_b32_e32 v31, v60
	v_mov_b32_e32 v58, v64
	v_mov_b32_e32 v59, v28
	v_pk_mul_f32 v[26:27], v[26:27], v[26:27]
	v_pk_fma_f32 v[30:31], v[176:177], v[30:31], v[58:59] neg_lo:[1,0,0] neg_hi:[1,0,0]
	v_mov_b32_e32 v60, v33
	v_mov_b32_e32 v28, v65
	v_pk_fma_f32 v[26:27], v[84:85], v[84:85], v[26:27]
	v_pk_fma_f32 v[28:29], v[176:177], v[60:61], v[28:29] neg_lo:[1,0,0] neg_hi:[1,0,0]
	v_pk_fma_f32 v[26:27], v[30:31], v[30:31], v[26:27]
	ds_read_b128 v[78:81], v91 offset:112
	v_pk_fma_f32 v[58:59], v[28:29], v[28:29], v[26:27]
	ds_read_b128 v[26:29], v91 offset:33808
	ds_read_b128 v[30:33], v91 offset:33792
	v_xor_b32_e32 v60, 1, v194
	v_cmp_lt_i32_e32 vcc, v60, v195
	v_pk_fma_f32 v[6:7], v[176:177], v[6:7], v[14:15] neg_lo:[1,0,0] neg_hi:[1,0,0]
	s_waitcnt lgkmcnt(1)
	v_pk_fma_f32 v[20:21], v[176:177], v[26:27], v[20:21] neg_lo:[1,0,0] neg_hi:[1,0,0]
	s_waitcnt lgkmcnt(0)
	v_pk_fma_f32 v[16:17], v[176:177], v[30:31], v[16:17] neg_lo:[1,0,0] neg_hi:[1,0,0]
	v_pk_fma_f32 v[18:19], v[176:177], v[32:33], v[18:19] neg_lo:[1,0,0] neg_hi:[1,0,0]
	v_mov_b32_e32 v32, v17
	v_mov_b32_e32 v33, v21
	v_pk_fma_f32 v[22:23], v[176:177], v[28:29], v[22:23] neg_lo:[1,0,0] neg_hi:[1,0,0]
	v_mov_b32_e32 v30, v16
	v_mov_b32_e32 v31, v20
	v_pk_mul_f32 v[32:33], v[32:33], v[32:33]
	v_mov_b32_e32 v26, v18
	v_mov_b32_e32 v27, v22
	v_pk_fma_f32 v[30:31], v[30:31], v[30:31], v[32:33]
	v_mov_b32_e32 v28, v19
	v_mov_b32_e32 v29, v23
	v_pk_fma_f32 v[26:27], v[26:27], v[26:27], v[30:31]
	v_cndmask_b32_e32 v60, v194, v60, vcc
	v_pk_fma_f32 v[26:27], v[28:29], v[28:29], v[26:27]
	v_lshlrev_b32_e32 v60, 2, v60
	v_add_f32_e32 v26, v26, v27
	v_add_f32_e32 v24, v26, v24
	v_add_f32_e32 v24, v24, v25
	v_add_f32_e32 v24, v24, v82
	v_add_f32_e32 v24, v24, v83
	v_add_f32_e32 v24, v24, v58
	v_add_f32_e32 v24, v24, v59
	ds_bpermute_b32 v25, v60, v24
	v_xor_b32_e32 v26, 2, v194
	v_cmp_lt_i32_e32 vcc, v26, v195
	v_pk_fma_f32 v[0:1], v[176:177], v[0:1], v[8:9] neg_lo:[1,0,0] neg_hi:[1,0,0]
	v_pk_fma_f32 v[8:9], v[176:177], v[42:43], v[50:51] neg_lo:[1,0,0] neg_hi:[1,0,0]
	v_cndmask_b32_e32 v26, v194, v26, vcc
	v_lshlrev_b32_e32 v26, 2, v26
	s_waitcnt lgkmcnt(0)
; __device__ __forceinline__ unsigned cvtpk(float lo, float hi) { f32x2_t v = {lo, hi}; bf16x2_t b = __builtin_convertvector(v, bf16x2_t); return __builtin_bit_cast(unsigned, b); }
; __device__ __forceinline__ void attn_item(const Params& p, unsigned char* smem, int b, int h, int qb, float lam) {
;     ...
;     ss += __shfl_xor(ss, 1); ss += __shfl_xor(ss, 2);
;     const float rsn = rsqrtf(ss * (1.f / 128.f) + 1e-6f) * 0.8f;
;     const float4* nw = (const float4*)(p.attn_norm_w + qq * 32);
;     uint4* dst = (uint4*)(AQ + (size_t)(b * LTOK + NMETA + t0 + q) * 1024 + h * 128 + qq * 32);
; #pragma unroll
;     for (int i = 0; i < 4; ++i) {
;       float4 a0 = o0[2 * i], c0 = o1[2 * i], a1 = o0[2 * i + 1], c1 = o1[2 * i + 1];
;       float4 w0 = nw[2 * i], w1 = nw[2 * i + 1];
;       uint4 o;
;       o.x = cvtpk((a0.x - lam * c0.x) * rsn * w0.x, (a0.y - lam * c0.y) * rsn * w0.y);
;       o.y = cvtpk((a0.z - lam * c0.z) * rsn * w0.z, (a0.w - lam * c0.w) * rsn * w0.w);
;       o.z = cvtpk((a1.x - lam * c1.x) * rsn * w1.x, (a1.y - lam * c1.y) * rsn * w1.y);
;       o.w = cvtpk((a1.z - lam * c1.z) * rsn * w1.z, (a1.w - lam * c1.w) * rsn * w1.w);
;       dst[i] = o;
;     }
	v_add_f32_e32 v27, v24, v25
	ds_bpermute_b32 v26, v26, v27
	v_add_u32_e32 v24, s18, v88
	v_ashrrev_i32_e32 v25, 31, v24
	v_lshlrev_b64 v[24:25], 11, v[24:25]
	v_lshl_add_u64 v[24:25], s[12:13], 0, v[24:25]
	s_waitcnt lgkmcnt(0)
	v_add_f32_e32 v26, v27, v26
	v_fmamk_f32 v26, v26, 0x3c000000, v196
	v_mul_f32_e32 v27, 0x4b800000, v26
	v_cmp_gt_f32_e32 vcc, s34, v26
	v_lshl_add_u64 v[24:25], v[24:25], 0, v[178:179]
	v_pk_fma_f32 v[12:13], v[176:177], v[46:47], v[54:55] neg_lo:[1,0,0] neg_hi:[1,0,0]
	v_cndmask_b32_e32 v26, v26, v27, vcc
	v_rsq_f32_e32 v26, v26
	v_pk_fma_f32 v[14:15], v[176:177], v[48:49], v[56:57] neg_lo:[1,0,0] neg_hi:[1,0,0]
	v_mul_f32_e32 v27, 0x45800000, v26
	v_cndmask_b32_e32 v26, v26, v27, vcc
	v_mul_f32_e32 v26, 0x3f4ccccd, v26
	v_pk_mul_f32 v[16:17], v[16:17], v[26:27] op_sel_hi:[1,0]
	v_pk_mul_f32 v[18:19], v[18:19], v[26:27] op_sel_hi:[1,0]
	s_waitcnt vmcnt(0)
	v_pk_mul_f32 v[16:17], v[38:39], v[16:17]
	v_pk_mul_f32 v[18:19], v[40:41], v[18:19]
	v_cvt_pk_bf16_f32 v16, v16, v17
	v_cvt_pk_bf16_f32 v17, v18, v19
	v_pk_mul_f32 v[18:19], v[20:21], v[26:27] op_sel_hi:[1,0]
	v_pk_mul_f32 v[20:21], v[22:23], v[26:27] op_sel_hi:[1,0]
	v_pk_mul_f32 v[18:19], v[34:35], v[18:19]
	v_pk_mul_f32 v[20:21], v[36:37], v[20:21]
	v_cvt_pk_bf16_f32 v18, v18, v19
	v_cvt_pk_bf16_f32 v19, v20, v21
	global_store_dwordx4 v[24:25], v[16:19], off
	v_pk_mul_f32 v[4:5], v[26:27], v[4:5] op_sel_hi:[0,1]
	v_pk_mul_f32 v[6:7], v[26:27], v[6:7] op_sel_hi:[0,1]
	v_pk_mul_f32 v[0:1], v[26:27], v[0:1] op_sel_hi:[0,1]
	v_pk_mul_f32 v[8:9], v[26:27], v[8:9] op_sel_hi:[0,1]
	v_pk_mul_f32 v[12:13], v[26:27], v[12:13] op_sel_hi:[0,1]
	v_pk_mul_f32 v[14:15], v[26:27], v[14:15] op_sel_hi:[0,1]
	v_pk_mul_f32 v[4:5], v[4:5], v[96:97]
	v_pk_mul_f32 v[6:7], v[6:7], v[98:99]
	v_pk_mul_f32 v[0:1], v[0:1], v[100:101]
	v_cvt_pk_bf16_f32 v4, v4, v5
	v_cvt_pk_bf16_f32 v5, v6, v7
	v_cvt_pk_bf16_f32 v6, v0, v1
	v_pk_fma_f32 v[0:1], v[176:177], v[2:3], v[10:11] neg_lo:[1,0,0] neg_hi:[1,0,0]
	v_pk_fma_f32 v[10:11], v[176:177], v[44:45], v[52:53] neg_lo:[1,0,0] neg_hi:[1,0,0]
	v_pk_mul_f32 v[0:1], v[26:27], v[0:1] op_sel_hi:[0,1]
	v_pk_mul_f32 v[0:1], v[0:1], v[102:103]
	v_pk_mul_f32 v[10:11], v[26:27], v[10:11] op_sel_hi:[0,1]
	v_cvt_pk_bf16_f32 v7, v0, v1
	global_store_dwordx4 v[24:25], v[4:7], off offset:16
	v_pk_mul_f32 v[0:1], v[8:9], v[104:105]
	v_pk_mul_f32 v[2:3], v[10:11], v[106:107]
	v_pk_mul_f32 v[4:5], v[12:13], v[108:109]
	v_pk_mul_f32 v[6:7], v[14:15], v[110:111]
	v_cvt_pk_bf16_f32 v0, v0, v1
	v_cvt_pk_bf16_f32 v1, v2, v3
	v_cvt_pk_bf16_f32 v2, v4, v5
	v_cvt_pk_bf16_f32 v3, v6, v7
	global_store_dwordx4 v[24:25], v[0:3], off offset:32
	v_pk_fma_f32 v[8:9], v[176:177], v[66:67], v[74:75] neg_lo:[1,0,0] neg_hi:[1,0,0]
	v_pk_fma_f32 v[10:11], v[176:177], v[68:69], v[76:77] neg_lo:[1,0,0] neg_hi:[1,0,0]
	v_pk_fma_f32 v[12:13], v[176:177], v[70:71], v[78:79] neg_lo:[1,0,0] neg_hi:[1,0,0]
	v_pk_fma_f32 v[14:15], v[176:177], v[72:73], v[80:81] neg_lo:[1,0,0] neg_hi:[1,0,0]
	v_pk_mul_f32 v[8:9], v[26:27], v[8:9] op_sel_hi:[0,1]
	v_pk_mul_f32 v[10:11], v[26:27], v[10:11] op_sel_hi:[0,1]
	v_pk_mul_f32 v[12:13], v[26:27], v[12:13] op_sel_hi:[0,1]
	v_pk_mul_f32 v[14:15], v[26:27], v[14:15] op_sel_hi:[0,1]
	v_pk_mul_f32 v[0:1], v[8:9], v[112:113]
	v_pk_mul_f32 v[2:3], v[10:11], v[114:115]
	v_pk_mul_f32 v[4:5], v[12:13], v[116:117]
	v_pk_mul_f32 v[6:7], v[14:15], v[118:119]
	v_cvt_pk_bf16_f32 v0, v0, v1
	v_cvt_pk_bf16_f32 v1, v2, v3
	v_cvt_pk_bf16_f32 v2, v4, v5
	v_cvt_pk_bf16_f32 v3, v6, v7
	global_store_dwordx4 v[24:25], v[0:3], off offset:48
	s_barrier
